# v41 with MFMA snake chains over all 16 accumulators, A-fragment (second operand) major
# speedup vs baseline: 1.0373x; 1.0015x over previous
.LBB0_159:
	s_add_u32 s0, s22, 0xfff80080
	s_addc_u32 s1, s23, -1
	s_add_i32 s51, 0, 0x10000
	s_cmp_eq_u32 s50, 28
	s_cselect_b32 s27, s15, s1
	s_cselect_b32 s26, s46, s0
	v_add_u32_e32 v140, s51, v143
	s_cselect_b32 s25, s13, s49
	s_cselect_b32 s24, s47, s48
	s_add_i32 s0, 0, 0x14000
	ds_read_b128 v[146:149], v140
	ds_read_b128 v[150:153], v140 offset:1024
	ds_read_b128 v[154:157], v140 offset:2048
	ds_read_b128 v[158:161], v140 offset:3072
	v_add_u32_e32 v140, s0, v143
	ds_read_b128 v[162:165], v140
	ds_read_b128 v[166:169], v140 offset:1024
	ds_read_b128 v[170:173], v140 offset:2048
	ds_read_b128 v[174:177], v140 offset:3072
	v_lshl_add_u64 v[140:141], s[22:23], 0, v[136:137]
	s_add_i32 m0, s35, 0xc000
	ds_read_b128 v[178:181], v144
	ds_read_b128 v[182:185], v144 offset:1024
	ds_read_b128 v[192:195], v144 offset:2048
	ds_read_b128 v[196:199], v144 offset:3072
	ds_read_b128 v[200:203], v144 offset:4096
	ds_read_b128 v[204:207], v144 offset:5120
	ds_read_b128 v[208:211], v144 offset:6144
	ds_read_b128 v[212:215], v144 offset:7168
	global_load_lds_dwordx4 v[140:141], off
	v_lshl_add_u64 v[140:141], s[22:23], 0, v[138:139]
	s_add_i32 m0, s35, 0xe000
	s_nop 0
	global_load_lds_dwordx4 v[140:141], off
	s_waitcnt vmcnt(8)
	s_waitcnt lgkmcnt(0)
	s_setprio 1
	s_barrier

	v_mfma_f32_16x16x32_bf16 v[126:129], v[146:149], v[178:181], v[126:129]
	v_mfma_f32_16x16x32_bf16 v[126:129], v[150:153], v[182:185], v[126:129]
	v_mfma_f32_16x16x32_bf16 v[118:121], v[158:161], v[182:185], v[118:121]
	v_mfma_f32_16x16x32_bf16 v[118:121], v[154:157], v[178:181], v[118:121]
	v_mfma_f32_16x16x32_bf16 v[122:125], v[162:165], v[178:181], v[122:125]
	v_mfma_f32_16x16x32_bf16 v[122:125], v[166:169], v[182:185], v[122:125]
	v_mfma_f32_16x16x32_bf16 v[114:117], v[174:177], v[182:185], v[114:117]
	v_mfma_f32_16x16x32_bf16 v[114:117], v[170:173], v[178:181], v[114:117]
	v_mfma_f32_16x16x32_bf16 v[98:101], v[170:173], v[192:195], v[98:101]
	v_mfma_f32_16x16x32_bf16 v[98:101], v[174:177], v[196:199], v[98:101]
	v_mfma_f32_16x16x32_bf16 v[106:109], v[166:169], v[196:199], v[106:109]
	v_mfma_f32_16x16x32_bf16 v[106:109], v[162:165], v[192:195], v[106:109]
	v_mfma_f32_16x16x32_bf16 v[102:105], v[154:157], v[192:195], v[102:105]
	v_mfma_f32_16x16x32_bf16 v[102:105], v[158:161], v[196:199], v[102:105]
	v_mfma_f32_16x16x32_bf16 v[110:113], v[150:153], v[196:199], v[110:113]
	v_mfma_f32_16x16x32_bf16 v[110:113], v[146:149], v[192:195], v[110:113]


	v_mfma_f32_16x16x32_bf16 v[94:97], v[146:149], v[200:203], v[94:97]
	v_mfma_f32_16x16x32_bf16 v[94:97], v[150:153], v[204:207], v[94:97]
	v_mfma_f32_16x16x32_bf16 v[86:89], v[158:161], v[204:207], v[86:89]
	v_mfma_f32_16x16x32_bf16 v[86:89], v[154:157], v[200:203], v[86:89]
	v_mfma_f32_16x16x32_bf16 v[90:93], v[162:165], v[200:203], v[90:93]
	v_mfma_f32_16x16x32_bf16 v[90:93], v[166:169], v[204:207], v[90:93]
	v_mfma_f32_16x16x32_bf16 v[82:85], v[174:177], v[204:207], v[82:85]
	v_mfma_f32_16x16x32_bf16 v[82:85], v[170:173], v[200:203], v[82:85]
	v_mfma_f32_16x16x32_bf16 v[66:69], v[170:173], v[208:211], v[66:69]
	v_mfma_f32_16x16x32_bf16 v[66:69], v[174:177], v[212:215], v[66:69]
	v_mfma_f32_16x16x32_bf16 v[74:77], v[166:169], v[212:215], v[74:77]
	v_mfma_f32_16x16x32_bf16 v[74:77], v[162:165], v[208:211], v[74:77]
	v_mfma_f32_16x16x32_bf16 v[70:73], v[154:157], v[208:211], v[70:73]
	v_mfma_f32_16x16x32_bf16 v[70:73], v[158:161], v[212:215], v[70:73]
	v_mfma_f32_16x16x32_bf16 v[78:81], v[150:153], v[212:215], v[78:81]
	v_mfma_f32_16x16x32_bf16 v[78:81], v[146:149], v[208:211], v[78:81]
	s_barrier
	s_setprio 0
	s_add_i32 s1, s51, s31
	v_lshl_add_u64 v[140:141], s[24:25], 0, v[186:187]
	s_mov_b32 m0, s1
	ds_read_b128 v[178:181], v144 offset:16384
	ds_read_b128 v[182:185], v144 offset:17408
	ds_read_b128 v[192:195], v144 offset:18432
	ds_read_b128 v[196:199], v144 offset:19456
	ds_read_b128 v[200:203], v144 offset:20480
	ds_read_b128 v[204:207], v144 offset:21504
	ds_read_b128 v[208:211], v144 offset:22528
	ds_read_b128 v[212:215], v144 offset:23552
	global_load_lds_dwordx4 v[140:141], off
	s_add_i32 m0, s1, 0x2000
	s_add_u32 s52, s24, 0x80000
	v_lshl_add_u64 v[216:217], s[24:25], 0, v[130:131]
	s_addc_u32 s53, s25, 0
	s_add_i32 s0, s0, s31
	global_load_lds_dwordx4 v[216:217], off
	v_lshl_add_u64 v[218:219], s[52:53], 0, v[186:187]
	s_mov_b32 m0, s0
	v_lshl_add_u64 v[220:221], s[26:27], 0, v[132:133]
	global_load_lds_dwordx4 v[218:219], off
	v_lshl_add_u64 v[218:219], s[52:53], 0, v[130:131]
	s_add_i32 m0, s0, 0x2000
	s_nop 0
	global_load_lds_dwordx4 v[218:219], off
	v_lshl_add_u64 v[218:219], s[26:27], 0, v[134:135]
	s_mov_b32 m0, s35
	s_nop 0
	global_load_lds_dwordx4 v[218:219], off
	s_mov_b32 m0, s36
	s_nop 0
	global_load_lds_dwordx4 v[220:221], off
	s_waitcnt vmcnt(8)
	s_waitcnt lgkmcnt(0)
	s_setprio 1
	s_barrier

	v_mfma_f32_16x16x32_bf16 v[62:65], v[146:149], v[178:181], v[62:65]
	v_mfma_f32_16x16x32_bf16 v[62:65], v[150:153], v[182:185], v[62:65]
	v_mfma_f32_16x16x32_bf16 v[54:57], v[158:161], v[182:185], v[54:57]
	v_mfma_f32_16x16x32_bf16 v[54:57], v[154:157], v[178:181], v[54:57]
	v_mfma_f32_16x16x32_bf16 v[58:61], v[162:165], v[178:181], v[58:61]
	v_mfma_f32_16x16x32_bf16 v[58:61], v[166:169], v[182:185], v[58:61]
	v_mfma_f32_16x16x32_bf16 v[50:53], v[174:177], v[182:185], v[50:53]
	v_mfma_f32_16x16x32_bf16 v[50:53], v[170:173], v[178:181], v[50:53]
	v_mfma_f32_16x16x32_bf16 v[34:37], v[170:173], v[192:195], v[34:37]
	v_mfma_f32_16x16x32_bf16 v[34:37], v[174:177], v[196:199], v[34:37]
	v_mfma_f32_16x16x32_bf16 v[42:45], v[166:169], v[196:199], v[42:45]
	v_mfma_f32_16x16x32_bf16 v[42:45], v[162:165], v[192:195], v[42:45]
	v_mfma_f32_16x16x32_bf16 v[38:41], v[154:157], v[192:195], v[38:41]
	v_mfma_f32_16x16x32_bf16 v[38:41], v[158:161], v[196:199], v[38:41]
	v_mfma_f32_16x16x32_bf16 v[46:49], v[150:153], v[196:199], v[46:49]
	v_mfma_f32_16x16x32_bf16 v[46:49], v[146:149], v[192:195], v[46:49]


	v_mfma_f32_16x16x32_bf16 v[30:33], v[146:149], v[200:203], v[30:33]
	v_mfma_f32_16x16x32_bf16 v[30:33], v[150:153], v[204:207], v[30:33]
	v_mfma_f32_16x16x32_bf16 v[22:25], v[158:161], v[204:207], v[22:25]
	v_mfma_f32_16x16x32_bf16 v[22:25], v[154:157], v[200:203], v[22:25]
	v_mfma_f32_16x16x32_bf16 v[26:29], v[162:165], v[200:203], v[26:29]
	v_mfma_f32_16x16x32_bf16 v[26:29], v[166:169], v[204:207], v[26:29]
	v_mfma_f32_16x16x32_bf16 v[18:21], v[174:177], v[204:207], v[18:21]
	v_mfma_f32_16x16x32_bf16 v[18:21], v[170:173], v[200:203], v[18:21]
	v_mfma_f32_16x16x32_bf16 v[2:5], v[170:173], v[208:211], v[2:5]
	v_mfma_f32_16x16x32_bf16 v[2:5], v[174:177], v[212:215], v[2:5]
	v_mfma_f32_16x16x32_bf16 v[10:13], v[166:169], v[212:215], v[10:13]
	v_mfma_f32_16x16x32_bf16 v[10:13], v[162:165], v[208:211], v[10:13]
	v_mfma_f32_16x16x32_bf16 v[6:9], v[154:157], v[208:211], v[6:9]
	v_mfma_f32_16x16x32_bf16 v[6:9], v[158:161], v[212:215], v[6:9]
	v_mfma_f32_16x16x32_bf16 v[14:17], v[150:153], v[212:215], v[14:17]
	v_mfma_f32_16x16x32_bf16 v[14:17], v[146:149], v[208:211], v[14:17]
	s_barrier
	s_setprio 0
	s_add_i32 s0, 0, 0x18000
	v_add_u32_e32 v145, s0, v143
	s_add_i32 s1, 0, 0x1c000
	ds_read_b128 v[146:149], v145
	ds_read_b128 v[150:153], v145 offset:1024
	ds_read_b128 v[154:157], v145 offset:2048
	ds_read_b128 v[158:161], v145 offset:3072
	v_add_u32_e32 v145, s1, v143
	ds_read_b128 v[162:165], v145
	ds_read_b128 v[166:169], v145 offset:1024
	ds_read_b128 v[170:173], v145 offset:2048
	ds_read_b128 v[174:177], v145 offset:3072
	s_add_u32 s26, s26, 0x80000
	s_addc_u32 s27, s27, 0
	s_mov_b32 m0, s37
	v_lshl_add_u64 v[222:223], s[26:27], 0, v[134:135]
	ds_read_b128 v[178:181], v144 offset:32768
	ds_read_b128 v[182:185], v144 offset:33792
	ds_read_b128 v[192:195], v144 offset:34816
	ds_read_b128 v[196:199], v144 offset:35840
	ds_read_b128 v[200:203], v144 offset:36864
	ds_read_b128 v[204:207], v144 offset:37888
	ds_read_b128 v[208:211], v144 offset:38912
	ds_read_b128 v[212:215], v144 offset:39936
	global_load_lds_dwordx4 v[222:223], off
	v_lshl_add_u64 v[222:223], s[26:27], 0, v[132:133]
	s_mov_b32 m0, s38
	s_nop 0
	global_load_lds_dwordx4 v[222:223], off
	s_waitcnt vmcnt(8)
	s_waitcnt lgkmcnt(0)
	s_setprio 1
	s_barrier

	v_mfma_f32_16x16x32_bf16 v[126:129], v[146:149], v[178:181], v[126:129]
	v_mfma_f32_16x16x32_bf16 v[126:129], v[150:153], v[182:185], v[126:129]
	v_mfma_f32_16x16x32_bf16 v[118:121], v[158:161], v[182:185], v[118:121]
	v_mfma_f32_16x16x32_bf16 v[118:121], v[154:157], v[178:181], v[118:121]
	v_mfma_f32_16x16x32_bf16 v[122:125], v[162:165], v[178:181], v[122:125]
	v_mfma_f32_16x16x32_bf16 v[122:125], v[166:169], v[182:185], v[122:125]
	v_mfma_f32_16x16x32_bf16 v[114:117], v[174:177], v[182:185], v[114:117]
	v_mfma_f32_16x16x32_bf16 v[114:117], v[170:173], v[178:181], v[114:117]
	v_mfma_f32_16x16x32_bf16 v[98:101], v[170:173], v[192:195], v[98:101]
	v_mfma_f32_16x16x32_bf16 v[98:101], v[174:177], v[196:199], v[98:101]
	v_mfma_f32_16x16x32_bf16 v[106:109], v[166:169], v[196:199], v[106:109]
	v_mfma_f32_16x16x32_bf16 v[106:109], v[162:165], v[192:195], v[106:109]
	v_mfma_f32_16x16x32_bf16 v[102:105], v[154:157], v[192:195], v[102:105]
	v_mfma_f32_16x16x32_bf16 v[102:105], v[158:161], v[196:199], v[102:105]
	v_mfma_f32_16x16x32_bf16 v[110:113], v[150:153], v[196:199], v[110:113]
	v_mfma_f32_16x16x32_bf16 v[110:113], v[146:149], v[192:195], v[110:113]


	v_mfma_f32_16x16x32_bf16 v[94:97], v[146:149], v[200:203], v[94:97]
	v_mfma_f32_16x16x32_bf16 v[94:97], v[150:153], v[204:207], v[94:97]
	v_mfma_f32_16x16x32_bf16 v[86:89], v[158:161], v[204:207], v[86:89]
	v_mfma_f32_16x16x32_bf16 v[86:89], v[154:157], v[200:203], v[86:89]
	v_mfma_f32_16x16x32_bf16 v[90:93], v[162:165], v[200:203], v[90:93]
	v_mfma_f32_16x16x32_bf16 v[90:93], v[166:169], v[204:207], v[90:93]
	v_mfma_f32_16x16x32_bf16 v[82:85], v[174:177], v[204:207], v[82:85]
	v_mfma_f32_16x16x32_bf16 v[82:85], v[170:173], v[200:203], v[82:85]
	v_mfma_f32_16x16x32_bf16 v[66:69], v[170:173], v[208:211], v[66:69]
	v_mfma_f32_16x16x32_bf16 v[66:69], v[174:177], v[212:215], v[66:69]
	v_mfma_f32_16x16x32_bf16 v[74:77], v[166:169], v[212:215], v[74:77]
	v_mfma_f32_16x16x32_bf16 v[74:77], v[162:165], v[208:211], v[74:77]
	v_mfma_f32_16x16x32_bf16 v[70:73], v[154:157], v[208:211], v[70:73]
	v_mfma_f32_16x16x32_bf16 v[70:73], v[158:161], v[212:215], v[70:73]
	v_mfma_f32_16x16x32_bf16 v[78:81], v[150:153], v[212:215], v[78:81]
	v_mfma_f32_16x16x32_bf16 v[78:81], v[146:149], v[208:211], v[78:81]
	s_barrier
	s_setprio 0
	s_add_i32 s0, s0, s31
	v_lshl_add_u64 v[140:141], v[140:141], 0, s[84:85]
	s_mov_b32 m0, s0
	ds_read_b128 v[178:181], v144 offset:49152
	ds_read_b128 v[182:185], v144 offset:50176
	ds_read_b128 v[192:195], v144 offset:51200
	ds_read_b128 v[196:199], v144 offset:52224
	ds_read_b128 v[200:203], v144 offset:53248
	ds_read_b128 v[204:207], v144 offset:54272
	ds_read_b128 v[208:211], v144 offset:55296
	ds_read_b128 v[212:215], v144 offset:56320
	global_load_lds_dwordx4 v[140:141], off
	s_add_i32 m0, s0, 0x2000
	s_add_u32 s24, s24, 0x80080
	v_lshl_add_u64 v[140:141], v[216:217], 0, s[84:85]
	s_addc_u32 s25, s25, 0
	s_add_i32 s0, s1, s31
	global_load_lds_dwordx4 v[140:141], off
	v_lshl_add_u64 v[140:141], s[24:25], 0, v[186:187]
	s_mov_b32 m0, s0
	s_nop 0
	global_load_lds_dwordx4 v[140:141], off
	v_lshl_add_u64 v[140:141], s[24:25], 0, v[130:131]
	s_add_i32 m0, s0, 0x2000
	s_nop 0
	global_load_lds_dwordx4 v[140:141], off
	v_lshl_add_u64 v[140:141], v[218:219], 0, s[84:85]
	s_mov_b32 m0, s39
	s_nop 0
	global_load_lds_dwordx4 v[140:141], off
	v_lshl_add_u64 v[140:141], v[220:221], 0, s[84:85]
	s_mov_b32 m0, s40
	s_nop 0
	global_load_lds_dwordx4 v[140:141], off
	s_waitcnt vmcnt(8)
	s_waitcnt lgkmcnt(0)
	s_setprio 1
	s_barrier

	v_mfma_f32_16x16x32_bf16 v[62:65], v[146:149], v[178:181], v[62:65]
	v_mfma_f32_16x16x32_bf16 v[62:65], v[150:153], v[182:185], v[62:65]
	v_mfma_f32_16x16x32_bf16 v[54:57], v[158:161], v[182:185], v[54:57]
	v_mfma_f32_16x16x32_bf16 v[54:57], v[154:157], v[178:181], v[54:57]
	v_mfma_f32_16x16x32_bf16 v[58:61], v[162:165], v[178:181], v[58:61]
	v_mfma_f32_16x16x32_bf16 v[58:61], v[166:169], v[182:185], v[58:61]
	v_mfma_f32_16x16x32_bf16 v[50:53], v[174:177], v[182:185], v[50:53]
	v_mfma_f32_16x16x32_bf16 v[50:53], v[170:173], v[178:181], v[50:53]
	v_mfma_f32_16x16x32_bf16 v[34:37], v[170:173], v[192:195], v[34:37]
	v_mfma_f32_16x16x32_bf16 v[34:37], v[174:177], v[196:199], v[34:37]
	v_mfma_f32_16x16x32_bf16 v[42:45], v[166:169], v[196:199], v[42:45]
	v_mfma_f32_16x16x32_bf16 v[42:45], v[162:165], v[192:195], v[42:45]
	v_mfma_f32_16x16x32_bf16 v[38:41], v[154:157], v[192:195], v[38:41]
	v_mfma_f32_16x16x32_bf16 v[38:41], v[158:161], v[196:199], v[38:41]
	v_mfma_f32_16x16x32_bf16 v[46:49], v[150:153], v[196:199], v[46:49]
	v_mfma_f32_16x16x32_bf16 v[46:49], v[146:149], v[192:195], v[46:49]


	v_mfma_f32_16x16x32_bf16 v[30:33], v[146:149], v[200:203], v[30:33]
	v_mfma_f32_16x16x32_bf16 v[30:33], v[150:153], v[204:207], v[30:33]
	v_mfma_f32_16x16x32_bf16 v[22:25], v[158:161], v[204:207], v[22:25]
	v_mfma_f32_16x16x32_bf16 v[22:25], v[154:157], v[200:203], v[22:25]
	v_mfma_f32_16x16x32_bf16 v[26:29], v[162:165], v[200:203], v[26:29]
	v_mfma_f32_16x16x32_bf16 v[26:29], v[166:169], v[204:207], v[26:29]
	v_mfma_f32_16x16x32_bf16 v[18:21], v[174:177], v[204:207], v[18:21]
	v_mfma_f32_16x16x32_bf16 v[18:21], v[170:173], v[200:203], v[18:21]
	v_mfma_f32_16x16x32_bf16 v[2:5], v[170:173], v[208:211], v[2:5]
	v_mfma_f32_16x16x32_bf16 v[2:5], v[174:177], v[212:215], v[2:5]
	v_mfma_f32_16x16x32_bf16 v[10:13], v[166:169], v[212:215], v[10:13]
	v_mfma_f32_16x16x32_bf16 v[10:13], v[162:165], v[208:211], v[10:13]
	v_mfma_f32_16x16x32_bf16 v[6:9], v[154:157], v[208:211], v[6:9]
	v_mfma_f32_16x16x32_bf16 v[6:9], v[158:161], v[212:215], v[6:9]
	v_mfma_f32_16x16x32_bf16 v[14:17], v[150:153], v[212:215], v[14:17]
	v_mfma_f32_16x16x32_bf16 v[14:17], v[146:149], v[208:211], v[14:17]
	s_barrier
	s_setprio 0
	s_add_i32 s50, s50, 2
	s_add_u32 s22, s22, 0x100
	s_addc_u32 s23, s23, 0
	s_add_u32 s48, s48, 0x100
	s_addc_u32 s49, s49, 0
	s_cmp_gt_u32 s50, 29
	s_cbranch_scc0 .LBB0_159
	s_and_b64 vcc, exec, s[10:11]
	s_cbranch_vccz .LBB0_162
	s_barrier

.LBB0_243:
	s_add_u32 s22, s20, 0x100
	s_addc_u32 s23, s21, 0
	s_add_i32 s0, 0, 0x10000
	s_cmpk_eq_i32 s51, 0x54
	s_cselect_b32 s27, s7, s23
	s_cselect_b32 s26, s6, s22
	s_cselect_b32 s25, s19, s50
	s_cselect_b32 s24, s18, s49
	s_add_i32 s1, 0, 0x14000
	v_add_u32_e32 v126, s0, v237
	v_add_u32_e32 v158, s1, v237
	ds_read_b128 v[90:93], v126
	ds_read_b128 v[102:105], v126 offset:1024
	ds_read_b128 v[114:117], v126 offset:2048
	ds_read_b128 v[126:129], v126 offset:3072
	ds_read_b128 v[138:141], v158
	ds_read_b128 v[142:145], v158 offset:1024
	ds_read_b128 v[154:157], v158 offset:2048
	ds_read_b128 v[158:161], v158 offset:3072
	v_lshl_add_u64 v[210:211], s[20:21], 0, v[198:199]
	s_add_i32 m0, s34, 0xc000
	ds_read_b128 v[162:165], v238
	ds_read_b128 v[166:169], v238 offset:1024
	ds_read_b128 v[170:173], v238 offset:2048
	ds_read_b128 v[174:177], v238 offset:3072
	ds_read_b128 v[178:181], v238 offset:4096
	ds_read_b128 v[182:185], v238 offset:5120
	ds_read_b128 v[202:205], v238 offset:6144
	ds_read_b128 v[206:209], v238 offset:7168
	global_load_lds_dwordx4 v[210:211], off
	v_lshl_add_u64 v[210:211], s[20:21], 0, v[200:201]
	s_add_i32 m0, s34, 0xe000
	s_nop 0
	global_load_lds_dwordx4 v[210:211], off
	s_waitcnt vmcnt(8)
	s_waitcnt lgkmcnt(0)
	s_setprio 1
	s_barrier

	v_mfma_f32_16x16x32_bf16 v[150:153], v[90:93], v[162:165], v[150:153]
	v_mfma_f32_16x16x32_bf16 v[150:153], v[102:105], v[166:169], v[150:153]
	v_mfma_f32_16x16x32_bf16 v[146:149], v[126:129], v[166:169], v[146:149]
	v_mfma_f32_16x16x32_bf16 v[146:149], v[114:117], v[162:165], v[146:149]
	v_mfma_f32_16x16x32_bf16 v[134:137], v[138:141], v[162:165], v[134:137]
	v_mfma_f32_16x16x32_bf16 v[134:137], v[142:145], v[166:169], v[134:137]
	v_mfma_f32_16x16x32_bf16 v[130:133], v[158:161], v[166:169], v[130:133]
	v_mfma_f32_16x16x32_bf16 v[130:133], v[154:157], v[162:165], v[130:133]
	v_mfma_f32_16x16x32_bf16 v[106:109], v[154:157], v[170:173], v[106:109]
	v_mfma_f32_16x16x32_bf16 v[106:109], v[158:161], v[174:177], v[106:109]
	v_mfma_f32_16x16x32_bf16 v[110:113], v[142:145], v[174:177], v[110:113]
	v_mfma_f32_16x16x32_bf16 v[110:113], v[138:141], v[170:173], v[110:113]
	v_mfma_f32_16x16x32_bf16 v[118:121], v[114:117], v[170:173], v[118:121]
	v_mfma_f32_16x16x32_bf16 v[118:121], v[126:129], v[174:177], v[118:121]
	v_mfma_f32_16x16x32_bf16 v[122:125], v[102:105], v[174:177], v[122:125]
	v_mfma_f32_16x16x32_bf16 v[122:125], v[90:93], v[170:173], v[122:125]


	v_mfma_f32_16x16x32_bf16 v[98:101], v[90:93], v[178:181], v[98:101]
	v_mfma_f32_16x16x32_bf16 v[98:101], v[102:105], v[182:185], v[98:101]
	v_mfma_f32_16x16x32_bf16 v[94:97], v[126:129], v[182:185], v[94:97]
	v_mfma_f32_16x16x32_bf16 v[94:97], v[114:117], v[178:181], v[94:97]
	v_mfma_f32_16x16x32_bf16 v[86:89], v[138:141], v[178:181], v[86:89]
	v_mfma_f32_16x16x32_bf16 v[86:89], v[142:145], v[182:185], v[86:89]
	v_mfma_f32_16x16x32_bf16 v[82:85], v[158:161], v[182:185], v[82:85]
	v_mfma_f32_16x16x32_bf16 v[82:85], v[154:157], v[178:181], v[82:85]
	v_mfma_f32_16x16x32_bf16 v[66:69], v[154:157], v[202:205], v[66:69]
	v_mfma_f32_16x16x32_bf16 v[66:69], v[158:161], v[206:209], v[66:69]
	v_mfma_f32_16x16x32_bf16 v[70:73], v[142:145], v[206:209], v[70:73]
	v_mfma_f32_16x16x32_bf16 v[70:73], v[138:141], v[202:205], v[70:73]
	v_mfma_f32_16x16x32_bf16 v[74:77], v[114:117], v[202:205], v[74:77]
	v_mfma_f32_16x16x32_bf16 v[74:77], v[126:129], v[206:209], v[74:77]
	v_mfma_f32_16x16x32_bf16 v[78:81], v[102:105], v[206:209], v[78:81]
	v_mfma_f32_16x16x32_bf16 v[78:81], v[90:93], v[202:205], v[78:81]
	s_barrier
	s_setprio 0
	s_add_i32 s0, s0, s31
	v_lshl_add_u64 v[210:211], s[24:25], 0, v[186:187]
	s_mov_b32 m0, s0
	ds_read_b128 v[162:165], v238 offset:16384
	ds_read_b128 v[166:169], v238 offset:17408
	ds_read_b128 v[170:173], v238 offset:18432
	ds_read_b128 v[174:177], v238 offset:19456
	ds_read_b128 v[178:181], v238 offset:20480
	ds_read_b128 v[182:185], v238 offset:21504
	ds_read_b128 v[202:205], v238 offset:22528
	ds_read_b128 v[206:209], v238 offset:23552
	global_load_lds_dwordx4 v[210:211], off
	s_add_i32 m0, s0, 0x2000
	s_add_u32 s20, s24, 0x160000
	v_lshl_add_u64 v[212:213], s[24:25], 0, v[196:197]
	s_addc_u32 s21, s25, 0
	s_add_i32 s0, s1, s31
	global_load_lds_dwordx4 v[212:213], off
	v_lshl_add_u64 v[214:215], s[20:21], 0, v[186:187]
	s_mov_b32 m0, s0
	v_lshl_add_u64 v[216:217], s[26:27], 0, v[194:195]
	global_load_lds_dwordx4 v[214:215], off
	v_lshl_add_u64 v[214:215], s[20:21], 0, v[196:197]
	s_add_i32 m0, s0, 0x2000
	s_nop 0
	global_load_lds_dwordx4 v[214:215], off
	v_lshl_add_u64 v[214:215], s[26:27], 0, v[192:193]
	s_mov_b32 m0, s34
	s_nop 0
	global_load_lds_dwordx4 v[214:215], off
	s_mov_b32 m0, s35
	s_nop 0
	global_load_lds_dwordx4 v[216:217], off
	s_waitcnt vmcnt(8)
	s_waitcnt lgkmcnt(0)
	s_setprio 1
	s_barrier

	v_mfma_f32_16x16x32_bf16 v[62:65], v[90:93], v[162:165], v[62:65]
	v_mfma_f32_16x16x32_bf16 v[62:65], v[102:105], v[166:169], v[62:65]
	v_mfma_f32_16x16x32_bf16 v[58:61], v[126:129], v[166:169], v[58:61]
	v_mfma_f32_16x16x32_bf16 v[58:61], v[114:117], v[162:165], v[58:61]
	v_mfma_f32_16x16x32_bf16 v[54:57], v[138:141], v[162:165], v[54:57]
	v_mfma_f32_16x16x32_bf16 v[54:57], v[142:145], v[166:169], v[54:57]
	v_mfma_f32_16x16x32_bf16 v[50:53], v[158:161], v[166:169], v[50:53]
	v_mfma_f32_16x16x32_bf16 v[50:53], v[154:157], v[162:165], v[50:53]
	v_mfma_f32_16x16x32_bf16 v[34:37], v[154:157], v[170:173], v[34:37]
	v_mfma_f32_16x16x32_bf16 v[34:37], v[158:161], v[174:177], v[34:37]
	v_mfma_f32_16x16x32_bf16 v[38:41], v[142:145], v[174:177], v[38:41]
	v_mfma_f32_16x16x32_bf16 v[38:41], v[138:141], v[170:173], v[38:41]
	v_mfma_f32_16x16x32_bf16 v[42:45], v[114:117], v[170:173], v[42:45]
	v_mfma_f32_16x16x32_bf16 v[42:45], v[126:129], v[174:177], v[42:45]
	v_mfma_f32_16x16x32_bf16 v[46:49], v[102:105], v[174:177], v[46:49]
	v_mfma_f32_16x16x32_bf16 v[46:49], v[90:93], v[170:173], v[46:49]


	v_mfma_f32_16x16x32_bf16 v[30:33], v[90:93], v[178:181], v[30:33]
	v_mfma_f32_16x16x32_bf16 v[30:33], v[102:105], v[182:185], v[30:33]
	v_mfma_f32_16x16x32_bf16 v[26:29], v[126:129], v[182:185], v[26:29]
	v_mfma_f32_16x16x32_bf16 v[26:29], v[114:117], v[178:181], v[26:29]
	v_mfma_f32_16x16x32_bf16 v[22:25], v[138:141], v[178:181], v[22:25]
	v_mfma_f32_16x16x32_bf16 v[22:25], v[142:145], v[182:185], v[22:25]
	v_mfma_f32_16x16x32_bf16 v[18:21], v[158:161], v[182:185], v[18:21]
	v_mfma_f32_16x16x32_bf16 v[18:21], v[154:157], v[178:181], v[18:21]
	v_mfma_f32_16x16x32_bf16 v[2:5], v[154:157], v[202:205], v[2:5]
	v_mfma_f32_16x16x32_bf16 v[2:5], v[158:161], v[206:209], v[2:5]
	v_mfma_f32_16x16x32_bf16 v[6:9], v[142:145], v[206:209], v[6:9]
	v_mfma_f32_16x16x32_bf16 v[6:9], v[138:141], v[202:205], v[6:9]
	v_mfma_f32_16x16x32_bf16 v[10:13], v[114:117], v[202:205], v[10:13]
	v_mfma_f32_16x16x32_bf16 v[10:13], v[126:129], v[206:209], v[10:13]
	v_mfma_f32_16x16x32_bf16 v[14:17], v[102:105], v[206:209], v[14:17]
	v_mfma_f32_16x16x32_bf16 v[14:17], v[90:93], v[202:205], v[14:17]
	s_barrier
	s_setprio 0
	s_add_i32 s0, 0, 0x18000
	s_add_i32 s1, 0, 0x1c000
	v_add_u32_e32 v126, s0, v237
	v_add_u32_e32 v158, s1, v237
	ds_read_b128 v[90:93], v126
	ds_read_b128 v[102:105], v126 offset:1024
	ds_read_b128 v[114:117], v126 offset:2048
	ds_read_b128 v[126:129], v126 offset:3072
	ds_read_b128 v[138:141], v158
	ds_read_b128 v[142:145], v158 offset:1024
	ds_read_b128 v[154:157], v158 offset:2048
	ds_read_b128 v[158:161], v158 offset:3072
	s_add_u32 s20, s26, 0x160000
	s_addc_u32 s21, s27, 0
	s_mov_b32 m0, s36
	v_lshl_add_u64 v[218:219], s[20:21], 0, v[192:193]
	ds_read_b128 v[162:165], v238 offset:32768
	ds_read_b128 v[166:169], v238 offset:33792
	ds_read_b128 v[170:173], v238 offset:34816
	ds_read_b128 v[174:177], v238 offset:35840
	ds_read_b128 v[178:181], v238 offset:36864
	ds_read_b128 v[182:185], v238 offset:37888
	ds_read_b128 v[202:205], v238 offset:38912
	ds_read_b128 v[206:209], v238 offset:39936
	global_load_lds_dwordx4 v[218:219], off
	v_lshl_add_u64 v[218:219], s[20:21], 0, v[194:195]
	s_mov_b32 m0, s37
	s_nop 0
	global_load_lds_dwordx4 v[218:219], off
	s_waitcnt vmcnt(8)
	s_waitcnt lgkmcnt(0)
	s_setprio 1
	s_barrier

	v_mfma_f32_16x16x32_bf16 v[150:153], v[90:93], v[162:165], v[150:153]
	v_mfma_f32_16x16x32_bf16 v[150:153], v[102:105], v[166:169], v[150:153]
	v_mfma_f32_16x16x32_bf16 v[146:149], v[126:129], v[166:169], v[146:149]
	v_mfma_f32_16x16x32_bf16 v[146:149], v[114:117], v[162:165], v[146:149]
	v_mfma_f32_16x16x32_bf16 v[134:137], v[138:141], v[162:165], v[134:137]
	v_mfma_f32_16x16x32_bf16 v[134:137], v[142:145], v[166:169], v[134:137]
	v_mfma_f32_16x16x32_bf16 v[130:133], v[158:161], v[166:169], v[130:133]
	v_mfma_f32_16x16x32_bf16 v[130:133], v[154:157], v[162:165], v[130:133]
	v_mfma_f32_16x16x32_bf16 v[106:109], v[154:157], v[170:173], v[106:109]
	v_mfma_f32_16x16x32_bf16 v[106:109], v[158:161], v[174:177], v[106:109]
	v_mfma_f32_16x16x32_bf16 v[110:113], v[142:145], v[174:177], v[110:113]
	v_mfma_f32_16x16x32_bf16 v[110:113], v[138:141], v[170:173], v[110:113]
	v_mfma_f32_16x16x32_bf16 v[118:121], v[114:117], v[170:173], v[118:121]
	v_mfma_f32_16x16x32_bf16 v[118:121], v[126:129], v[174:177], v[118:121]
	v_mfma_f32_16x16x32_bf16 v[122:125], v[102:105], v[174:177], v[122:125]
	v_mfma_f32_16x16x32_bf16 v[122:125], v[90:93], v[170:173], v[122:125]


	v_mfma_f32_16x16x32_bf16 v[98:101], v[90:93], v[178:181], v[98:101]
	v_mfma_f32_16x16x32_bf16 v[98:101], v[102:105], v[182:185], v[98:101]
	v_mfma_f32_16x16x32_bf16 v[94:97], v[126:129], v[182:185], v[94:97]
	v_mfma_f32_16x16x32_bf16 v[94:97], v[114:117], v[178:181], v[94:97]
	v_mfma_f32_16x16x32_bf16 v[86:89], v[138:141], v[178:181], v[86:89]
	v_mfma_f32_16x16x32_bf16 v[86:89], v[142:145], v[182:185], v[86:89]
	v_mfma_f32_16x16x32_bf16 v[82:85], v[158:161], v[182:185], v[82:85]
	v_mfma_f32_16x16x32_bf16 v[82:85], v[154:157], v[178:181], v[82:85]
	v_mfma_f32_16x16x32_bf16 v[66:69], v[154:157], v[202:205], v[66:69]
	v_mfma_f32_16x16x32_bf16 v[66:69], v[158:161], v[206:209], v[66:69]
	v_mfma_f32_16x16x32_bf16 v[70:73], v[142:145], v[206:209], v[70:73]
	v_mfma_f32_16x16x32_bf16 v[70:73], v[138:141], v[202:205], v[70:73]
	v_mfma_f32_16x16x32_bf16 v[74:77], v[114:117], v[202:205], v[74:77]
	v_mfma_f32_16x16x32_bf16 v[74:77], v[126:129], v[206:209], v[74:77]
	v_mfma_f32_16x16x32_bf16 v[78:81], v[102:105], v[206:209], v[78:81]
	v_mfma_f32_16x16x32_bf16 v[78:81], v[90:93], v[202:205], v[78:81]
	s_barrier
	s_setprio 0
	s_add_i32 s0, s0, s31
	v_lshl_add_u64 v[210:211], v[210:211], 0, s[84:85]
	s_mov_b32 m0, s0
	ds_read_b128 v[162:165], v238 offset:49152
	ds_read_b128 v[166:169], v238 offset:50176
	ds_read_b128 v[170:173], v238 offset:51200
	ds_read_b128 v[174:177], v238 offset:52224
	ds_read_b128 v[178:181], v238 offset:53248
	ds_read_b128 v[182:185], v238 offset:54272
	ds_read_b128 v[202:205], v238 offset:55296
	ds_read_b128 v[206:209], v238 offset:56320
	global_load_lds_dwordx4 v[210:211], off
	s_add_i32 m0, s0, 0x2000
	s_add_u32 s20, s24, 0x160080
	v_lshl_add_u64 v[210:211], v[212:213], 0, s[84:85]
	s_addc_u32 s21, s25, 0
	s_add_i32 s0, s1, s31
	global_load_lds_dwordx4 v[210:211], off
	v_lshl_add_u64 v[210:211], s[20:21], 0, v[186:187]
	s_mov_b32 m0, s0
	s_nop 0
	global_load_lds_dwordx4 v[210:211], off
	v_lshl_add_u64 v[210:211], s[20:21], 0, v[196:197]
	s_add_i32 m0, s0, 0x2000
	s_nop 0
	global_load_lds_dwordx4 v[210:211], off
	v_lshl_add_u64 v[210:211], v[214:215], 0, s[84:85]
	s_mov_b32 m0, s41
	s_nop 0
	global_load_lds_dwordx4 v[210:211], off
	v_lshl_add_u64 v[210:211], v[216:217], 0, s[84:85]
	s_mov_b32 m0, s42
	s_nop 0
	global_load_lds_dwordx4 v[210:211], off
	s_waitcnt vmcnt(8)
	s_waitcnt lgkmcnt(0)
	s_setprio 1
	s_barrier

	v_mfma_f32_16x16x32_bf16 v[62:65], v[90:93], v[162:165], v[62:65]
	v_mfma_f32_16x16x32_bf16 v[62:65], v[102:105], v[166:169], v[62:65]
	v_mfma_f32_16x16x32_bf16 v[58:61], v[126:129], v[166:169], v[58:61]
	v_mfma_f32_16x16x32_bf16 v[58:61], v[114:117], v[162:165], v[58:61]
	v_mfma_f32_16x16x32_bf16 v[54:57], v[138:141], v[162:165], v[54:57]
	v_mfma_f32_16x16x32_bf16 v[54:57], v[142:145], v[166:169], v[54:57]
	v_mfma_f32_16x16x32_bf16 v[50:53], v[158:161], v[166:169], v[50:53]
	v_mfma_f32_16x16x32_bf16 v[50:53], v[154:157], v[162:165], v[50:53]
	v_mfma_f32_16x16x32_bf16 v[34:37], v[154:157], v[170:173], v[34:37]
	v_mfma_f32_16x16x32_bf16 v[34:37], v[158:161], v[174:177], v[34:37]
	v_mfma_f32_16x16x32_bf16 v[38:41], v[142:145], v[174:177], v[38:41]
	v_mfma_f32_16x16x32_bf16 v[38:41], v[138:141], v[170:173], v[38:41]
	v_mfma_f32_16x16x32_bf16 v[42:45], v[114:117], v[170:173], v[42:45]
	v_mfma_f32_16x16x32_bf16 v[42:45], v[126:129], v[174:177], v[42:45]
	v_mfma_f32_16x16x32_bf16 v[46:49], v[102:105], v[174:177], v[46:49]
	v_mfma_f32_16x16x32_bf16 v[46:49], v[90:93], v[170:173], v[46:49]


	v_mfma_f32_16x16x32_bf16 v[30:33], v[90:93], v[178:181], v[30:33]
	v_mfma_f32_16x16x32_bf16 v[30:33], v[102:105], v[182:185], v[30:33]
	v_mfma_f32_16x16x32_bf16 v[26:29], v[126:129], v[182:185], v[26:29]
	v_mfma_f32_16x16x32_bf16 v[26:29], v[114:117], v[178:181], v[26:29]
	v_mfma_f32_16x16x32_bf16 v[22:25], v[138:141], v[178:181], v[22:25]
	v_mfma_f32_16x16x32_bf16 v[22:25], v[142:145], v[182:185], v[22:25]
	v_mfma_f32_16x16x32_bf16 v[18:21], v[158:161], v[182:185], v[18:21]
	v_mfma_f32_16x16x32_bf16 v[18:21], v[154:157], v[178:181], v[18:21]
	v_mfma_f32_16x16x32_bf16 v[2:5], v[154:157], v[202:205], v[2:5]
	v_mfma_f32_16x16x32_bf16 v[2:5], v[158:161], v[206:209], v[2:5]
	v_mfma_f32_16x16x32_bf16 v[6:9], v[142:145], v[206:209], v[6:9]
	v_mfma_f32_16x16x32_bf16 v[6:9], v[138:141], v[202:205], v[6:9]
	v_mfma_f32_16x16x32_bf16 v[10:13], v[114:117], v[202:205], v[10:13]
	v_mfma_f32_16x16x32_bf16 v[10:13], v[126:129], v[206:209], v[10:13]
	v_mfma_f32_16x16x32_bf16 v[14:17], v[102:105], v[206:209], v[14:17]
	v_mfma_f32_16x16x32_bf16 v[14:17], v[90:93], v[202:205], v[14:17]
	s_barrier
	s_setprio 0
	s_add_i32 s51, s51, 2
	s_add_u32 s49, s49, 0x100
	s_addc_u32 s50, s50, 0
	s_cmpk_gt_u32 s51, 0x55
	s_mov_b64 s[20:21], s[22:23]
	s_cbranch_scc0 .LBB0_243
	s_and_b64 vcc, exec, s[16:17]
	s_cbranch_vccz .LBB0_246
	s_barrier

.LBB0_443:
	s_add_u32 s0, s26, 0xfff80080
	s_addc_u32 s1, s27, -1
	s_add_i32 s56, 0, 0x10000
	s_cmp_eq_u32 s55, 28
	s_cselect_b32 s31, s19, s1
	s_cselect_b32 s30, s51, s0
	v_add_u32_e32 v140, s56, v144
	s_cselect_b32 s29, s17, s54
	s_cselect_b32 s28, s52, s53
	s_add_i32 s0, 0, 0x14000
	ds_read_b128 v[146:149], v140
	ds_read_b128 v[150:153], v140 offset:1024
	ds_read_b128 v[154:157], v140 offset:2048
	ds_read_b128 v[158:161], v140 offset:3072
	v_add_u32_e32 v140, s0, v144
	ds_read_b128 v[162:165], v140
	ds_read_b128 v[166:169], v140 offset:1024
	ds_read_b128 v[170:173], v140 offset:2048
	ds_read_b128 v[174:177], v140 offset:3072
	v_lshl_add_u64 v[140:141], s[26:27], 0, v[136:137]
	s_add_i32 m0, s25, 0xc000
	ds_read_b128 v[178:181], v145
	ds_read_b128 v[182:185], v145 offset:1024
	ds_read_b128 v[192:195], v145 offset:2048
	ds_read_b128 v[196:199], v145 offset:3072
	ds_read_b128 v[200:203], v145 offset:4096
	ds_read_b128 v[204:207], v145 offset:5120
	ds_read_b128 v[208:211], v145 offset:6144
	ds_read_b128 v[212:215], v145 offset:7168
	global_load_lds_dwordx4 v[140:141], off
	v_lshl_add_u64 v[140:141], s[26:27], 0, v[138:139]
	s_add_i32 m0, s25, 0xe000
	s_nop 0
	global_load_lds_dwordx4 v[140:141], off
	s_waitcnt vmcnt(8)
	s_waitcnt lgkmcnt(0)
	s_setprio 1
	s_barrier

	v_mfma_f32_16x16x32_bf16 v[126:129], v[146:149], v[178:181], v[126:129]
	v_mfma_f32_16x16x32_bf16 v[126:129], v[150:153], v[182:185], v[126:129]
	v_mfma_f32_16x16x32_bf16 v[122:125], v[158:161], v[182:185], v[122:125]
	v_mfma_f32_16x16x32_bf16 v[122:125], v[154:157], v[178:181], v[122:125]
	v_mfma_f32_16x16x32_bf16 v[118:121], v[162:165], v[178:181], v[118:121]
	v_mfma_f32_16x16x32_bf16 v[118:121], v[166:169], v[182:185], v[118:121]
	v_mfma_f32_16x16x32_bf16 v[110:113], v[174:177], v[182:185], v[110:113]
	v_mfma_f32_16x16x32_bf16 v[110:113], v[170:173], v[178:181], v[110:113]
	v_mfma_f32_16x16x32_bf16 v[94:97], v[170:173], v[192:195], v[94:97]
	v_mfma_f32_16x16x32_bf16 v[94:97], v[174:177], v[196:199], v[94:97]
	v_mfma_f32_16x16x32_bf16 v[102:105], v[166:169], v[196:199], v[102:105]
	v_mfma_f32_16x16x32_bf16 v[102:105], v[162:165], v[192:195], v[102:105]
	v_mfma_f32_16x16x32_bf16 v[106:109], v[154:157], v[192:195], v[106:109]
	v_mfma_f32_16x16x32_bf16 v[106:109], v[158:161], v[196:199], v[106:109]
	v_mfma_f32_16x16x32_bf16 v[114:117], v[150:153], v[196:199], v[114:117]
	v_mfma_f32_16x16x32_bf16 v[114:117], v[146:149], v[192:195], v[114:117]


	v_mfma_f32_16x16x32_bf16 v[98:101], v[146:149], v[200:203], v[98:101]
	v_mfma_f32_16x16x32_bf16 v[98:101], v[150:153], v[204:207], v[98:101]
	v_mfma_f32_16x16x32_bf16 v[90:93], v[158:161], v[204:207], v[90:93]
	v_mfma_f32_16x16x32_bf16 v[90:93], v[154:157], v[200:203], v[90:93]
	v_mfma_f32_16x16x32_bf16 v[86:89], v[162:165], v[200:203], v[86:89]
	v_mfma_f32_16x16x32_bf16 v[86:89], v[166:169], v[204:207], v[86:89]
	v_mfma_f32_16x16x32_bf16 v[78:81], v[174:177], v[204:207], v[78:81]
	v_mfma_f32_16x16x32_bf16 v[78:81], v[170:173], v[200:203], v[78:81]
	v_mfma_f32_16x16x32_bf16 v[66:69], v[170:173], v[208:211], v[66:69]
	v_mfma_f32_16x16x32_bf16 v[66:69], v[174:177], v[212:215], v[66:69]
	v_mfma_f32_16x16x32_bf16 v[70:73], v[166:169], v[212:215], v[70:73]
	v_mfma_f32_16x16x32_bf16 v[70:73], v[162:165], v[208:211], v[70:73]
	v_mfma_f32_16x16x32_bf16 v[74:77], v[154:157], v[208:211], v[74:77]
	v_mfma_f32_16x16x32_bf16 v[74:77], v[158:161], v[212:215], v[74:77]
	v_mfma_f32_16x16x32_bf16 v[82:85], v[150:153], v[212:215], v[82:85]
	v_mfma_f32_16x16x32_bf16 v[82:85], v[146:149], v[208:211], v[82:85]
	s_barrier
	s_setprio 0
	s_add_i32 s1, s56, s39
	v_lshl_add_u64 v[140:141], s[28:29], 0, v[186:187]
	s_mov_b32 m0, s1
	ds_read_b128 v[178:181], v145 offset:16384
	ds_read_b128 v[182:185], v145 offset:17408
	ds_read_b128 v[192:195], v145 offset:18432
	ds_read_b128 v[196:199], v145 offset:19456
	ds_read_b128 v[200:203], v145 offset:20480
	ds_read_b128 v[204:207], v145 offset:21504
	ds_read_b128 v[208:211], v145 offset:22528
	ds_read_b128 v[212:215], v145 offset:23552
	global_load_lds_dwordx4 v[140:141], off
	s_add_i32 m0, s1, 0x2000
	s_add_u32 s56, s28, 0x80000
	v_lshl_add_u64 v[188:189], s[28:29], 0, v[130:131]
	s_addc_u32 s57, s29, 0
	s_add_i32 s0, s0, s39
	global_load_lds_dwordx4 v[188:189], off
	v_lshl_add_u64 v[216:217], s[56:57], 0, v[186:187]
	s_mov_b32 m0, s0
	v_lshl_add_u64 v[218:219], s[30:31], 0, v[132:133]
	global_load_lds_dwordx4 v[216:217], off
	v_lshl_add_u64 v[216:217], s[56:57], 0, v[130:131]
	s_add_i32 m0, s0, 0x2000
	s_nop 0
	global_load_lds_dwordx4 v[216:217], off
	v_lshl_add_u64 v[216:217], s[30:31], 0, v[134:135]
	s_mov_b32 m0, s25
	s_nop 0
	global_load_lds_dwordx4 v[216:217], off
	s_mov_b32 m0, s40
	s_nop 0
	global_load_lds_dwordx4 v[218:219], off
	s_waitcnt vmcnt(8)
	s_waitcnt lgkmcnt(0)
	s_setprio 1
	s_barrier

	v_mfma_f32_16x16x32_bf16 v[62:65], v[146:149], v[178:181], v[62:65]
	v_mfma_f32_16x16x32_bf16 v[62:65], v[150:153], v[182:185], v[62:65]
	v_mfma_f32_16x16x32_bf16 v[58:61], v[158:161], v[182:185], v[58:61]
	v_mfma_f32_16x16x32_bf16 v[58:61], v[154:157], v[178:181], v[58:61]
	v_mfma_f32_16x16x32_bf16 v[54:57], v[162:165], v[178:181], v[54:57]
	v_mfma_f32_16x16x32_bf16 v[54:57], v[166:169], v[182:185], v[54:57]
	v_mfma_f32_16x16x32_bf16 v[46:49], v[174:177], v[182:185], v[46:49]
	v_mfma_f32_16x16x32_bf16 v[46:49], v[170:173], v[178:181], v[46:49]
	v_mfma_f32_16x16x32_bf16 v[30:33], v[170:173], v[192:195], v[30:33]
	v_mfma_f32_16x16x32_bf16 v[30:33], v[174:177], v[196:199], v[30:33]
	v_mfma_f32_16x16x32_bf16 v[38:41], v[166:169], v[196:199], v[38:41]
	v_mfma_f32_16x16x32_bf16 v[38:41], v[162:165], v[192:195], v[38:41]
	v_mfma_f32_16x16x32_bf16 v[42:45], v[154:157], v[192:195], v[42:45]
	v_mfma_f32_16x16x32_bf16 v[42:45], v[158:161], v[196:199], v[42:45]
	v_mfma_f32_16x16x32_bf16 v[50:53], v[150:153], v[196:199], v[50:53]
	v_mfma_f32_16x16x32_bf16 v[50:53], v[146:149], v[192:195], v[50:53]


	v_mfma_f32_16x16x32_bf16 v[34:37], v[146:149], v[200:203], v[34:37]
	v_mfma_f32_16x16x32_bf16 v[34:37], v[150:153], v[204:207], v[34:37]
	v_mfma_f32_16x16x32_bf16 v[26:29], v[158:161], v[204:207], v[26:29]
	v_mfma_f32_16x16x32_bf16 v[26:29], v[154:157], v[200:203], v[26:29]
	v_mfma_f32_16x16x32_bf16 v[22:25], v[162:165], v[200:203], v[22:25]
	v_mfma_f32_16x16x32_bf16 v[22:25], v[166:169], v[204:207], v[22:25]
	v_mfma_f32_16x16x32_bf16 v[14:17], v[174:177], v[204:207], v[14:17]
	v_mfma_f32_16x16x32_bf16 v[14:17], v[170:173], v[200:203], v[14:17]
	v_mfma_f32_16x16x32_bf16 v[2:5], v[170:173], v[208:211], v[2:5]
	v_mfma_f32_16x16x32_bf16 v[2:5], v[174:177], v[212:215], v[2:5]
	v_mfma_f32_16x16x32_bf16 v[6:9], v[166:169], v[212:215], v[6:9]
	v_mfma_f32_16x16x32_bf16 v[6:9], v[162:165], v[208:211], v[6:9]
	v_mfma_f32_16x16x32_bf16 v[10:13], v[154:157], v[208:211], v[10:13]
	v_mfma_f32_16x16x32_bf16 v[10:13], v[158:161], v[212:215], v[10:13]
	v_mfma_f32_16x16x32_bf16 v[18:21], v[150:153], v[212:215], v[18:21]
	v_mfma_f32_16x16x32_bf16 v[18:21], v[146:149], v[208:211], v[18:21]
	s_barrier
	s_setprio 0
	s_add_i32 s0, 0, 0x18000
	s_add_i32 s1, 0, 0x1c000
	v_add_u32_e32 v158, s0, v144
	v_add_u32_e32 v174, s1, v144
	ds_read_b128 v[146:149], v158
	ds_read_b128 v[150:153], v158 offset:1024
	ds_read_b128 v[154:157], v158 offset:2048
	ds_read_b128 v[158:161], v158 offset:3072
	ds_read_b128 v[162:165], v174
	ds_read_b128 v[166:169], v174 offset:1024
	ds_read_b128 v[170:173], v174 offset:2048
	ds_read_b128 v[174:177], v174 offset:3072
	s_add_u32 s30, s30, 0x80000
	s_addc_u32 s31, s31, 0
	s_mov_b32 m0, s41
	v_lshl_add_u64 v[220:221], s[30:31], 0, v[134:135]
	ds_read_b128 v[178:181], v145 offset:32768
	ds_read_b128 v[182:185], v145 offset:33792
	ds_read_b128 v[192:195], v145 offset:34816
	ds_read_b128 v[196:199], v145 offset:35840
	ds_read_b128 v[200:203], v145 offset:36864
	ds_read_b128 v[204:207], v145 offset:37888
	ds_read_b128 v[208:211], v145 offset:38912
	ds_read_b128 v[212:215], v145 offset:39936
	global_load_lds_dwordx4 v[220:221], off
	v_lshl_add_u64 v[220:221], s[30:31], 0, v[132:133]
	s_mov_b32 m0, s42
	s_nop 0
	global_load_lds_dwordx4 v[220:221], off
	s_waitcnt vmcnt(8)
	s_waitcnt lgkmcnt(0)
	s_setprio 1
	s_barrier

	v_mfma_f32_16x16x32_bf16 v[126:129], v[146:149], v[178:181], v[126:129]
	v_mfma_f32_16x16x32_bf16 v[126:129], v[150:153], v[182:185], v[126:129]
	v_mfma_f32_16x16x32_bf16 v[122:125], v[158:161], v[182:185], v[122:125]
	v_mfma_f32_16x16x32_bf16 v[122:125], v[154:157], v[178:181], v[122:125]
	v_mfma_f32_16x16x32_bf16 v[118:121], v[162:165], v[178:181], v[118:121]
	v_mfma_f32_16x16x32_bf16 v[118:121], v[166:169], v[182:185], v[118:121]
	v_mfma_f32_16x16x32_bf16 v[110:113], v[174:177], v[182:185], v[110:113]
	v_mfma_f32_16x16x32_bf16 v[110:113], v[170:173], v[178:181], v[110:113]
	v_mfma_f32_16x16x32_bf16 v[94:97], v[170:173], v[192:195], v[94:97]
	v_mfma_f32_16x16x32_bf16 v[94:97], v[174:177], v[196:199], v[94:97]
	v_mfma_f32_16x16x32_bf16 v[102:105], v[166:169], v[196:199], v[102:105]
	v_mfma_f32_16x16x32_bf16 v[102:105], v[162:165], v[192:195], v[102:105]
	v_mfma_f32_16x16x32_bf16 v[106:109], v[154:157], v[192:195], v[106:109]
	v_mfma_f32_16x16x32_bf16 v[106:109], v[158:161], v[196:199], v[106:109]
	v_mfma_f32_16x16x32_bf16 v[114:117], v[150:153], v[196:199], v[114:117]
	v_mfma_f32_16x16x32_bf16 v[114:117], v[146:149], v[192:195], v[114:117]


	v_mfma_f32_16x16x32_bf16 v[98:101], v[146:149], v[200:203], v[98:101]
	v_mfma_f32_16x16x32_bf16 v[98:101], v[150:153], v[204:207], v[98:101]
	v_mfma_f32_16x16x32_bf16 v[90:93], v[158:161], v[204:207], v[90:93]
	v_mfma_f32_16x16x32_bf16 v[90:93], v[154:157], v[200:203], v[90:93]
	v_mfma_f32_16x16x32_bf16 v[86:89], v[162:165], v[200:203], v[86:89]
	v_mfma_f32_16x16x32_bf16 v[86:89], v[166:169], v[204:207], v[86:89]
	v_mfma_f32_16x16x32_bf16 v[78:81], v[174:177], v[204:207], v[78:81]
	v_mfma_f32_16x16x32_bf16 v[78:81], v[170:173], v[200:203], v[78:81]
	v_mfma_f32_16x16x32_bf16 v[66:69], v[170:173], v[208:211], v[66:69]
	v_mfma_f32_16x16x32_bf16 v[66:69], v[174:177], v[212:215], v[66:69]
	v_mfma_f32_16x16x32_bf16 v[70:73], v[166:169], v[212:215], v[70:73]
	v_mfma_f32_16x16x32_bf16 v[70:73], v[162:165], v[208:211], v[70:73]
	v_mfma_f32_16x16x32_bf16 v[74:77], v[154:157], v[208:211], v[74:77]
	v_mfma_f32_16x16x32_bf16 v[74:77], v[158:161], v[212:215], v[74:77]
	v_mfma_f32_16x16x32_bf16 v[82:85], v[150:153], v[212:215], v[82:85]
	v_mfma_f32_16x16x32_bf16 v[82:85], v[146:149], v[208:211], v[82:85]
	s_barrier
	s_setprio 0
	s_add_i32 s0, s0, s39
	v_lshl_add_u64 v[140:141], v[140:141], 0, s[84:85]
	s_mov_b32 m0, s0
	ds_read_b128 v[178:181], v145 offset:49152
	ds_read_b128 v[182:185], v145 offset:50176
	ds_read_b128 v[192:195], v145 offset:51200
	ds_read_b128 v[196:199], v145 offset:52224
	ds_read_b128 v[200:203], v145 offset:53248
	ds_read_b128 v[204:207], v145 offset:54272
	ds_read_b128 v[208:211], v145 offset:55296
	ds_read_b128 v[212:215], v145 offset:56320
	global_load_lds_dwordx4 v[140:141], off
	s_add_i32 m0, s0, 0x2000
	s_add_u32 s28, s28, 0x80080
	v_lshl_add_u64 v[140:141], v[188:189], 0, s[84:85]
	s_addc_u32 s29, s29, 0
	s_add_i32 s0, s1, s39
	global_load_lds_dwordx4 v[140:141], off
	v_lshl_add_u64 v[140:141], s[28:29], 0, v[186:187]
	s_mov_b32 m0, s0
	s_nop 0
	global_load_lds_dwordx4 v[140:141], off
	v_lshl_add_u64 v[140:141], s[28:29], 0, v[130:131]
	s_add_i32 m0, s0, 0x2000
	s_nop 0
	global_load_lds_dwordx4 v[140:141], off
	v_lshl_add_u64 v[140:141], v[216:217], 0, s[84:85]
	s_mov_b32 m0, s43
	s_nop 0
	global_load_lds_dwordx4 v[140:141], off
	v_lshl_add_u64 v[140:141], v[218:219], 0, s[84:85]
	s_mov_b32 m0, s44
	s_nop 0
	global_load_lds_dwordx4 v[140:141], off
	s_waitcnt vmcnt(8)
	s_waitcnt lgkmcnt(0)
	s_setprio 1
	s_barrier

	v_mfma_f32_16x16x32_bf16 v[62:65], v[146:149], v[178:181], v[62:65]
	v_mfma_f32_16x16x32_bf16 v[62:65], v[150:153], v[182:185], v[62:65]
	v_mfma_f32_16x16x32_bf16 v[58:61], v[158:161], v[182:185], v[58:61]
	v_mfma_f32_16x16x32_bf16 v[58:61], v[154:157], v[178:181], v[58:61]
	v_mfma_f32_16x16x32_bf16 v[54:57], v[162:165], v[178:181], v[54:57]
	v_mfma_f32_16x16x32_bf16 v[54:57], v[166:169], v[182:185], v[54:57]
	v_mfma_f32_16x16x32_bf16 v[46:49], v[174:177], v[182:185], v[46:49]
	v_mfma_f32_16x16x32_bf16 v[46:49], v[170:173], v[178:181], v[46:49]
	v_mfma_f32_16x16x32_bf16 v[30:33], v[170:173], v[192:195], v[30:33]
	v_mfma_f32_16x16x32_bf16 v[30:33], v[174:177], v[196:199], v[30:33]
	v_mfma_f32_16x16x32_bf16 v[38:41], v[166:169], v[196:199], v[38:41]
	v_mfma_f32_16x16x32_bf16 v[38:41], v[162:165], v[192:195], v[38:41]
	v_mfma_f32_16x16x32_bf16 v[42:45], v[154:157], v[192:195], v[42:45]
	v_mfma_f32_16x16x32_bf16 v[42:45], v[158:161], v[196:199], v[42:45]
	v_mfma_f32_16x16x32_bf16 v[50:53], v[150:153], v[196:199], v[50:53]
	v_mfma_f32_16x16x32_bf16 v[50:53], v[146:149], v[192:195], v[50:53]


	v_mfma_f32_16x16x32_bf16 v[34:37], v[146:149], v[200:203], v[34:37]
	v_mfma_f32_16x16x32_bf16 v[34:37], v[150:153], v[204:207], v[34:37]
	v_mfma_f32_16x16x32_bf16 v[26:29], v[158:161], v[204:207], v[26:29]
	v_mfma_f32_16x16x32_bf16 v[26:29], v[154:157], v[200:203], v[26:29]
	v_mfma_f32_16x16x32_bf16 v[22:25], v[162:165], v[200:203], v[22:25]
	v_mfma_f32_16x16x32_bf16 v[22:25], v[166:169], v[204:207], v[22:25]
	v_mfma_f32_16x16x32_bf16 v[14:17], v[174:177], v[204:207], v[14:17]
	v_mfma_f32_16x16x32_bf16 v[14:17], v[170:173], v[200:203], v[14:17]
	v_mfma_f32_16x16x32_bf16 v[2:5], v[170:173], v[208:211], v[2:5]
	v_mfma_f32_16x16x32_bf16 v[2:5], v[174:177], v[212:215], v[2:5]
	v_mfma_f32_16x16x32_bf16 v[6:9], v[166:169], v[212:215], v[6:9]
	v_mfma_f32_16x16x32_bf16 v[6:9], v[162:165], v[208:211], v[6:9]
	v_mfma_f32_16x16x32_bf16 v[10:13], v[154:157], v[208:211], v[10:13]
	v_mfma_f32_16x16x32_bf16 v[10:13], v[158:161], v[212:215], v[10:13]
	v_mfma_f32_16x16x32_bf16 v[18:21], v[150:153], v[212:215], v[18:21]
	v_mfma_f32_16x16x32_bf16 v[18:21], v[146:149], v[208:211], v[18:21]
	s_barrier
	s_setprio 0
	s_add_i32 s55, s55, 2
	s_add_u32 s26, s26, 0x100
	s_addc_u32 s27, s27, 0
	s_add_u32 s53, s53, 0x100
	s_addc_u32 s54, s54, 0
	s_cmp_gt_u32 s55, 29
	s_cbranch_scc0 .LBB0_443
	s_and_b64 vcc, exec, s[14:15]
	s_cbranch_vccz .LBB0_446
	s_barrier

.LBB0_1126:
	s_add_u32 s0, s28, 0xfff80080
	s_addc_u32 s1, s29, -1
	s_add_i32 s54, 0, 0x10000
	s_cmp_eq_u32 s53, 28
	s_cselect_b32 s35, s19, s1
	s_cselect_b32 s34, s25, s0
	s_cselect_b32 s31, s17, s52
	s_cselect_b32 s30, s27, s51
	s_add_i32 s55, 0, 0x14000
	v_add_u32_e32 v126, s54, v237
	v_add_u32_e32 v158, s55, v237
	ds_read_b128 v[90:93], v126
	ds_read_b128 v[102:105], v126 offset:1024
	ds_read_b128 v[114:117], v126 offset:2048
	ds_read_b128 v[126:129], v126 offset:3072
	ds_read_b128 v[138:141], v158
	ds_read_b128 v[142:145], v158 offset:1024
	ds_read_b128 v[154:157], v158 offset:2048
	ds_read_b128 v[158:161], v158 offset:3072
	v_lshl_add_u64 v[188:189], s[28:29], 0, v[198:199]
	s_add_i32 m0, s40, 0xc000
	ds_read_b128 v[162:165], v238
	ds_read_b128 v[166:169], v238 offset:1024
	ds_read_b128 v[170:173], v238 offset:2048
	ds_read_b128 v[174:177], v238 offset:3072
	ds_read_b128 v[178:181], v238 offset:4096
	ds_read_b128 v[182:185], v238 offset:5120
	ds_read_b128 v[202:205], v238 offset:6144
	ds_read_b128 v[206:209], v238 offset:7168
	global_load_lds_dwordx4 v[188:189], off
	v_lshl_add_u64 v[188:189], s[28:29], 0, v[200:201]
	s_add_i32 m0, s40, 0xe000
	s_nop 0
	global_load_lds_dwordx4 v[188:189], off
	s_waitcnt vmcnt(8)
	s_waitcnt lgkmcnt(0)
	s_setprio 1
	s_barrier

	v_mfma_f32_16x16x32_bf16 v[150:153], v[90:93], v[162:165], v[150:153]
	v_mfma_f32_16x16x32_bf16 v[150:153], v[102:105], v[166:169], v[150:153]
	v_mfma_f32_16x16x32_bf16 v[146:149], v[126:129], v[166:169], v[146:149]
	v_mfma_f32_16x16x32_bf16 v[146:149], v[114:117], v[162:165], v[146:149]
	v_mfma_f32_16x16x32_bf16 v[134:137], v[138:141], v[162:165], v[134:137]
	v_mfma_f32_16x16x32_bf16 v[134:137], v[142:145], v[166:169], v[134:137]
	v_mfma_f32_16x16x32_bf16 v[130:133], v[158:161], v[166:169], v[130:133]
	v_mfma_f32_16x16x32_bf16 v[130:133], v[154:157], v[162:165], v[130:133]
	v_mfma_f32_16x16x32_bf16 v[106:109], v[154:157], v[170:173], v[106:109]
	v_mfma_f32_16x16x32_bf16 v[106:109], v[158:161], v[174:177], v[106:109]
	v_mfma_f32_16x16x32_bf16 v[110:113], v[142:145], v[174:177], v[110:113]
	v_mfma_f32_16x16x32_bf16 v[110:113], v[138:141], v[170:173], v[110:113]
	v_mfma_f32_16x16x32_bf16 v[118:121], v[114:117], v[170:173], v[118:121]
	v_mfma_f32_16x16x32_bf16 v[118:121], v[126:129], v[174:177], v[118:121]
	v_mfma_f32_16x16x32_bf16 v[122:125], v[102:105], v[174:177], v[122:125]
	v_mfma_f32_16x16x32_bf16 v[122:125], v[90:93], v[170:173], v[122:125]


	v_mfma_f32_16x16x32_bf16 v[98:101], v[90:93], v[178:181], v[98:101]
	v_mfma_f32_16x16x32_bf16 v[98:101], v[102:105], v[182:185], v[98:101]
	v_mfma_f32_16x16x32_bf16 v[94:97], v[126:129], v[182:185], v[94:97]
	v_mfma_f32_16x16x32_bf16 v[94:97], v[114:117], v[178:181], v[94:97]
	v_mfma_f32_16x16x32_bf16 v[86:89], v[138:141], v[178:181], v[86:89]
	v_mfma_f32_16x16x32_bf16 v[86:89], v[142:145], v[182:185], v[86:89]
	v_mfma_f32_16x16x32_bf16 v[82:85], v[158:161], v[182:185], v[82:85]
	v_mfma_f32_16x16x32_bf16 v[82:85], v[154:157], v[178:181], v[82:85]
	v_mfma_f32_16x16x32_bf16 v[66:69], v[154:157], v[202:205], v[66:69]
	v_mfma_f32_16x16x32_bf16 v[66:69], v[158:161], v[206:209], v[66:69]
	v_mfma_f32_16x16x32_bf16 v[70:73], v[142:145], v[206:209], v[70:73]
	v_mfma_f32_16x16x32_bf16 v[70:73], v[138:141], v[202:205], v[70:73]
	v_mfma_f32_16x16x32_bf16 v[74:77], v[114:117], v[202:205], v[74:77]
	v_mfma_f32_16x16x32_bf16 v[74:77], v[126:129], v[206:209], v[74:77]
	v_mfma_f32_16x16x32_bf16 v[78:81], v[102:105], v[206:209], v[78:81]
	v_mfma_f32_16x16x32_bf16 v[78:81], v[90:93], v[202:205], v[78:81]
	s_barrier
	s_setprio 0
	s_add_i32 s0, s54, s39
	v_lshl_add_u64 v[188:189], s[30:31], 0, v[186:187]
	s_mov_b32 m0, s0
	ds_read_b128 v[162:165], v238 offset:16384
	ds_read_b128 v[166:169], v238 offset:17408
	ds_read_b128 v[170:173], v238 offset:18432
	ds_read_b128 v[174:177], v238 offset:19456
	ds_read_b128 v[178:181], v238 offset:20480
	ds_read_b128 v[182:185], v238 offset:21504
	ds_read_b128 v[202:205], v238 offset:22528
	ds_read_b128 v[206:209], v238 offset:23552
	global_load_lds_dwordx4 v[188:189], off
	s_add_i32 m0, s0, 0x2000
	s_add_u32 s0, s30, 0x80000
	v_lshl_add_u64 v[210:211], s[30:31], 0, v[196:197]
	s_addc_u32 s1, s31, 0
	s_add_i32 s54, s55, s39
	global_load_lds_dwordx4 v[210:211], off
	v_lshl_add_u64 v[212:213], s[0:1], 0, v[186:187]
	s_mov_b32 m0, s54
	v_lshl_add_u64 v[214:215], s[34:35], 0, v[194:195]
	global_load_lds_dwordx4 v[212:213], off
	v_lshl_add_u64 v[212:213], s[0:1], 0, v[196:197]
	s_add_i32 m0, s54, 0x2000
	s_nop 0
	global_load_lds_dwordx4 v[212:213], off
	v_lshl_add_u64 v[212:213], s[34:35], 0, v[192:193]
	s_mov_b32 m0, s40
	s_nop 0
	global_load_lds_dwordx4 v[212:213], off
	s_mov_b32 m0, s41
	s_nop 0
	global_load_lds_dwordx4 v[214:215], off
	s_waitcnt vmcnt(8)
	s_waitcnt lgkmcnt(0)
	s_setprio 1
	s_barrier

	v_mfma_f32_16x16x32_bf16 v[62:65], v[90:93], v[162:165], v[62:65]
	v_mfma_f32_16x16x32_bf16 v[62:65], v[102:105], v[166:169], v[62:65]
	v_mfma_f32_16x16x32_bf16 v[58:61], v[126:129], v[166:169], v[58:61]
	v_mfma_f32_16x16x32_bf16 v[58:61], v[114:117], v[162:165], v[58:61]
	v_mfma_f32_16x16x32_bf16 v[54:57], v[138:141], v[162:165], v[54:57]
	v_mfma_f32_16x16x32_bf16 v[54:57], v[142:145], v[166:169], v[54:57]
	v_mfma_f32_16x16x32_bf16 v[50:53], v[158:161], v[166:169], v[50:53]
	v_mfma_f32_16x16x32_bf16 v[50:53], v[154:157], v[162:165], v[50:53]
	v_mfma_f32_16x16x32_bf16 v[34:37], v[154:157], v[170:173], v[34:37]
	v_mfma_f32_16x16x32_bf16 v[34:37], v[158:161], v[174:177], v[34:37]
	v_mfma_f32_16x16x32_bf16 v[38:41], v[142:145], v[174:177], v[38:41]
	v_mfma_f32_16x16x32_bf16 v[38:41], v[138:141], v[170:173], v[38:41]
	v_mfma_f32_16x16x32_bf16 v[42:45], v[114:117], v[170:173], v[42:45]
	v_mfma_f32_16x16x32_bf16 v[42:45], v[126:129], v[174:177], v[42:45]
	v_mfma_f32_16x16x32_bf16 v[46:49], v[102:105], v[174:177], v[46:49]
	v_mfma_f32_16x16x32_bf16 v[46:49], v[90:93], v[170:173], v[46:49]


	v_mfma_f32_16x16x32_bf16 v[30:33], v[90:93], v[178:181], v[30:33]
	v_mfma_f32_16x16x32_bf16 v[30:33], v[102:105], v[182:185], v[30:33]
	v_mfma_f32_16x16x32_bf16 v[26:29], v[126:129], v[182:185], v[26:29]
	v_mfma_f32_16x16x32_bf16 v[26:29], v[114:117], v[178:181], v[26:29]
	v_mfma_f32_16x16x32_bf16 v[22:25], v[138:141], v[178:181], v[22:25]
	v_mfma_f32_16x16x32_bf16 v[22:25], v[142:145], v[182:185], v[22:25]
	v_mfma_f32_16x16x32_bf16 v[18:21], v[158:161], v[182:185], v[18:21]
	v_mfma_f32_16x16x32_bf16 v[18:21], v[154:157], v[178:181], v[18:21]
	v_mfma_f32_16x16x32_bf16 v[2:5], v[154:157], v[202:205], v[2:5]
	v_mfma_f32_16x16x32_bf16 v[2:5], v[158:161], v[206:209], v[2:5]
	v_mfma_f32_16x16x32_bf16 v[6:9], v[142:145], v[206:209], v[6:9]
	v_mfma_f32_16x16x32_bf16 v[6:9], v[138:141], v[202:205], v[6:9]
	v_mfma_f32_16x16x32_bf16 v[10:13], v[114:117], v[202:205], v[10:13]
	v_mfma_f32_16x16x32_bf16 v[10:13], v[126:129], v[206:209], v[10:13]
	v_mfma_f32_16x16x32_bf16 v[14:17], v[102:105], v[206:209], v[14:17]
	v_mfma_f32_16x16x32_bf16 v[14:17], v[90:93], v[202:205], v[14:17]
	s_barrier
	s_setprio 0
	s_add_i32 s54, 0, 0x18000
	s_add_i32 s55, 0, 0x1c000
	v_add_u32_e32 v126, s54, v237
	v_add_u32_e32 v158, s55, v237
	ds_read_b128 v[90:93], v126
	ds_read_b128 v[102:105], v126 offset:1024
	ds_read_b128 v[114:117], v126 offset:2048
	ds_read_b128 v[126:129], v126 offset:3072
	ds_read_b128 v[138:141], v158
	ds_read_b128 v[142:145], v158 offset:1024
	ds_read_b128 v[154:157], v158 offset:2048
	ds_read_b128 v[158:161], v158 offset:3072
	s_add_u32 s0, s34, 0x80000
	s_addc_u32 s1, s35, 0
	s_mov_b32 m0, s42
	v_lshl_add_u64 v[216:217], s[0:1], 0, v[192:193]
	ds_read_b128 v[162:165], v238 offset:32768
	ds_read_b128 v[166:169], v238 offset:33792
	ds_read_b128 v[170:173], v238 offset:34816
	ds_read_b128 v[174:177], v238 offset:35840
	ds_read_b128 v[178:181], v238 offset:36864
	ds_read_b128 v[182:185], v238 offset:37888
	ds_read_b128 v[202:205], v238 offset:38912
	ds_read_b128 v[206:209], v238 offset:39936
	global_load_lds_dwordx4 v[216:217], off
	v_lshl_add_u64 v[216:217], s[0:1], 0, v[194:195]
	s_mov_b32 m0, s43
	s_nop 0
	global_load_lds_dwordx4 v[216:217], off
	s_waitcnt vmcnt(8)
	s_waitcnt lgkmcnt(0)
	s_setprio 1
	s_barrier

	v_mfma_f32_16x16x32_bf16 v[150:153], v[90:93], v[162:165], v[150:153]
	v_mfma_f32_16x16x32_bf16 v[150:153], v[102:105], v[166:169], v[150:153]
	v_mfma_f32_16x16x32_bf16 v[146:149], v[126:129], v[166:169], v[146:149]
	v_mfma_f32_16x16x32_bf16 v[146:149], v[114:117], v[162:165], v[146:149]
	v_mfma_f32_16x16x32_bf16 v[134:137], v[138:141], v[162:165], v[134:137]
	v_mfma_f32_16x16x32_bf16 v[134:137], v[142:145], v[166:169], v[134:137]
	v_mfma_f32_16x16x32_bf16 v[130:133], v[158:161], v[166:169], v[130:133]
	v_mfma_f32_16x16x32_bf16 v[130:133], v[154:157], v[162:165], v[130:133]
	v_mfma_f32_16x16x32_bf16 v[106:109], v[154:157], v[170:173], v[106:109]
	v_mfma_f32_16x16x32_bf16 v[106:109], v[158:161], v[174:177], v[106:109]
	v_mfma_f32_16x16x32_bf16 v[110:113], v[142:145], v[174:177], v[110:113]
	v_mfma_f32_16x16x32_bf16 v[110:113], v[138:141], v[170:173], v[110:113]
	v_mfma_f32_16x16x32_bf16 v[118:121], v[114:117], v[170:173], v[118:121]
	v_mfma_f32_16x16x32_bf16 v[118:121], v[126:129], v[174:177], v[118:121]
	v_mfma_f32_16x16x32_bf16 v[122:125], v[102:105], v[174:177], v[122:125]
	v_mfma_f32_16x16x32_bf16 v[122:125], v[90:93], v[170:173], v[122:125]


	v_mfma_f32_16x16x32_bf16 v[98:101], v[90:93], v[178:181], v[98:101]
	v_mfma_f32_16x16x32_bf16 v[98:101], v[102:105], v[182:185], v[98:101]
	v_mfma_f32_16x16x32_bf16 v[94:97], v[126:129], v[182:185], v[94:97]
	v_mfma_f32_16x16x32_bf16 v[94:97], v[114:117], v[178:181], v[94:97]
	v_mfma_f32_16x16x32_bf16 v[86:89], v[138:141], v[178:181], v[86:89]
	v_mfma_f32_16x16x32_bf16 v[86:89], v[142:145], v[182:185], v[86:89]
	v_mfma_f32_16x16x32_bf16 v[82:85], v[158:161], v[182:185], v[82:85]
	v_mfma_f32_16x16x32_bf16 v[82:85], v[154:157], v[178:181], v[82:85]
	v_mfma_f32_16x16x32_bf16 v[66:69], v[154:157], v[202:205], v[66:69]
	v_mfma_f32_16x16x32_bf16 v[66:69], v[158:161], v[206:209], v[66:69]
	v_mfma_f32_16x16x32_bf16 v[70:73], v[142:145], v[206:209], v[70:73]
	v_mfma_f32_16x16x32_bf16 v[70:73], v[138:141], v[202:205], v[70:73]
	v_mfma_f32_16x16x32_bf16 v[74:77], v[114:117], v[202:205], v[74:77]
	v_mfma_f32_16x16x32_bf16 v[74:77], v[126:129], v[206:209], v[74:77]
	v_mfma_f32_16x16x32_bf16 v[78:81], v[102:105], v[206:209], v[78:81]
	v_mfma_f32_16x16x32_bf16 v[78:81], v[90:93], v[202:205], v[78:81]
	s_barrier
	s_setprio 0
	s_add_i32 s0, s54, s39
	v_lshl_add_u64 v[188:189], v[188:189], 0, s[84:85]
	s_mov_b32 m0, s0
	ds_read_b128 v[162:165], v238 offset:49152
	ds_read_b128 v[166:169], v238 offset:50176
	ds_read_b128 v[170:173], v238 offset:51200
	ds_read_b128 v[174:177], v238 offset:52224
	ds_read_b128 v[178:181], v238 offset:53248
	ds_read_b128 v[182:185], v238 offset:54272
	ds_read_b128 v[202:205], v238 offset:55296
	ds_read_b128 v[206:209], v238 offset:56320
	global_load_lds_dwordx4 v[188:189], off
	s_add_i32 m0, s0, 0x2000
	s_add_u32 s0, s30, 0x80080
	v_lshl_add_u64 v[188:189], v[210:211], 0, s[84:85]
	s_addc_u32 s1, s31, 0
	s_add_i32 s30, s55, s39
	global_load_lds_dwordx4 v[188:189], off
	v_lshl_add_u64 v[188:189], s[0:1], 0, v[186:187]
	s_mov_b32 m0, s30
	s_nop 0
	global_load_lds_dwordx4 v[188:189], off
	v_lshl_add_u64 v[188:189], s[0:1], 0, v[196:197]
	s_add_i32 m0, s30, 0x2000
	s_nop 0
	global_load_lds_dwordx4 v[188:189], off
	v_lshl_add_u64 v[188:189], v[212:213], 0, s[84:85]
	s_mov_b32 m0, s47
	s_nop 0
	global_load_lds_dwordx4 v[188:189], off
	v_lshl_add_u64 v[188:189], v[214:215], 0, s[84:85]
	s_mov_b32 m0, s48
	s_nop 0
	global_load_lds_dwordx4 v[188:189], off
	s_waitcnt vmcnt(8)
	s_waitcnt lgkmcnt(0)
	s_setprio 1
	s_barrier

	v_mfma_f32_16x16x32_bf16 v[62:65], v[90:93], v[162:165], v[62:65]
	v_mfma_f32_16x16x32_bf16 v[62:65], v[102:105], v[166:169], v[62:65]
	v_mfma_f32_16x16x32_bf16 v[58:61], v[126:129], v[166:169], v[58:61]
	v_mfma_f32_16x16x32_bf16 v[58:61], v[114:117], v[162:165], v[58:61]
	v_mfma_f32_16x16x32_bf16 v[54:57], v[138:141], v[162:165], v[54:57]
	v_mfma_f32_16x16x32_bf16 v[54:57], v[142:145], v[166:169], v[54:57]
	v_mfma_f32_16x16x32_bf16 v[50:53], v[158:161], v[166:169], v[50:53]
	v_mfma_f32_16x16x32_bf16 v[50:53], v[154:157], v[162:165], v[50:53]
	v_mfma_f32_16x16x32_bf16 v[34:37], v[154:157], v[170:173], v[34:37]
	v_mfma_f32_16x16x32_bf16 v[34:37], v[158:161], v[174:177], v[34:37]
	v_mfma_f32_16x16x32_bf16 v[38:41], v[142:145], v[174:177], v[38:41]
	v_mfma_f32_16x16x32_bf16 v[38:41], v[138:141], v[170:173], v[38:41]
	v_mfma_f32_16x16x32_bf16 v[42:45], v[114:117], v[170:173], v[42:45]
	v_mfma_f32_16x16x32_bf16 v[42:45], v[126:129], v[174:177], v[42:45]
	v_mfma_f32_16x16x32_bf16 v[46:49], v[102:105], v[174:177], v[46:49]
	v_mfma_f32_16x16x32_bf16 v[46:49], v[90:93], v[170:173], v[46:49]


	v_mfma_f32_16x16x32_bf16 v[30:33], v[90:93], v[178:181], v[30:33]
	v_mfma_f32_16x16x32_bf16 v[30:33], v[102:105], v[182:185], v[30:33]
	v_mfma_f32_16x16x32_bf16 v[26:29], v[126:129], v[182:185], v[26:29]
	v_mfma_f32_16x16x32_bf16 v[26:29], v[114:117], v[178:181], v[26:29]
	v_mfma_f32_16x16x32_bf16 v[22:25], v[138:141], v[178:181], v[22:25]
	v_mfma_f32_16x16x32_bf16 v[22:25], v[142:145], v[182:185], v[22:25]
	v_mfma_f32_16x16x32_bf16 v[18:21], v[158:161], v[182:185], v[18:21]
	v_mfma_f32_16x16x32_bf16 v[18:21], v[154:157], v[178:181], v[18:21]
	v_mfma_f32_16x16x32_bf16 v[2:5], v[154:157], v[202:205], v[2:5]
	v_mfma_f32_16x16x32_bf16 v[2:5], v[158:161], v[206:209], v[2:5]
	v_mfma_f32_16x16x32_bf16 v[6:9], v[142:145], v[206:209], v[6:9]
	v_mfma_f32_16x16x32_bf16 v[6:9], v[138:141], v[202:205], v[6:9]
	v_mfma_f32_16x16x32_bf16 v[10:13], v[114:117], v[202:205], v[10:13]
	v_mfma_f32_16x16x32_bf16 v[10:13], v[126:129], v[206:209], v[10:13]
	v_mfma_f32_16x16x32_bf16 v[14:17], v[102:105], v[206:209], v[14:17]
	v_mfma_f32_16x16x32_bf16 v[14:17], v[90:93], v[202:205], v[14:17]
	s_barrier
	s_setprio 0
	s_add_i32 s53, s53, 2
	s_add_u32 s28, s28, 0x100
	s_addc_u32 s29, s29, 0
	s_add_u32 s51, s51, 0x100
	s_addc_u32 s52, s52, 0
	s_cmp_gt_u32 s53, 29
	s_cbranch_scc0 .LBB0_1126
	s_and_b64 vcc, exec, s[14:15]
	s_cbranch_vccz .LBB0_1129
	s_barrier
